# sel loop row sum: scalar v_add_f32 pairs instead of v_pk_add_f32 (bit-identical, cheaper issue)
# speedup vs baseline: 1.0048x; 1.0048x over previous
.Lsel_nodiag_0b:
	v_add_u32_e32 v187, s81, v208
	ds_read_b128 v[124:127], v187 offset:9216
	ds_read_b128 v[144:147], v187 offset:13824
	ds_read_b128 v[148:151], v187 offset:9248
	v_exp_f32_e32 v80, v80
	v_exp_f32_e32 v81, v81
	v_exp_f32_e32 v82, v82
	v_exp_f32_e32 v83, v83
	s_waitcnt lgkmcnt(6)
	v_mfma_f32_32x32x16_bf16 v[238:253], v[108:111], v[128:131], v[2:17]
	ds_read_b128 v[108:111], v0 offset:64
	v_exp_f32_e32 v84, v84
	v_exp_f32_e32 v85, v85
	v_exp_f32_e32 v86, v86
	v_exp_f32_e32 v87, v87
	s_waitcnt lgkmcnt(6)
	v_mfma_f32_32x32x16_bf16 v[222:237], v[112:115], v[128:131], v[2:17]
	ds_read_b128 v[112:115], v0 offset:4672
	v_add_f32_e32 v164, 0, v80
	v_add_f32_e32 v165, 0, v81
	v_add_f32_e32 v164, v82, v164
	v_add_f32_e32 v165, v83, v165
	v_cvt_pk_bf16_f32 v80, v80, v81
	v_cvt_pk_bf16_f32 v81, v82, v83
	v_add_f32_e32 v164, v84, v164
	v_add_f32_e32 v165, v85, v165
	v_add_f32_e32 v164, v86, v164
	v_add_f32_e32 v165, v87, v165
	v_cvt_pk_bf16_f32 v82, v84, v85
	v_cvt_pk_bf16_f32 v83, v86, v87
	v_cndmask_b32_e64 v80, v80, 0, s[72:73]
	v_cndmask_b32_e64 v81, v81, 0, s[72:73]
	v_cndmask_b32_e64 v82, v82, 0, s[72:73]
	v_cndmask_b32_e64 v83, v83, 0, s[72:73]
	v_exp_f32_e32 v88, v88
	v_exp_f32_e32 v89, v89
	s_waitcnt lgkmcnt(4)
	v_mfma_f32_32x32x16_bf16 v[48:63], v[124:127], v[80:83], v[48:63]
	ds_read_b128 v[124:127], v187 offset:13856
	v_exp_f32_e32 v90, v90
	v_exp_f32_e32 v91, v91
	s_waitcnt lgkmcnt(4)
	v_mfma_f32_32x32x16_bf16 v[32:47], v[144:147], v[80:83], v[32:47]
	ds_read_b128 v[144:147], v187 offset:9280
	v_exp_f32_e32 v92, v92
	v_exp_f32_e32 v93, v93
	v_mfma_f32_32x32x16_bf16 v[238:253], v[116:119], v[132:135], v[238:253]
	ds_read_b128 v[116:119], v0 offset:96
	v_exp_f32_e32 v94, v94
	v_exp_f32_e32 v95, v95
	v_mfma_f32_32x32x16_bf16 v[222:237], v[120:123], v[132:135], v[222:237]
	ds_read_b128 v[120:123], v0 offset:4704
	v_add_f32_e32 v164, v88, v164
	v_add_f32_e32 v165, v89, v165
	v_add_f32_e32 v164, v90, v164
	v_add_f32_e32 v165, v91, v165
	v_cvt_pk_bf16_f32 v88, v88, v89
	v_cvt_pk_bf16_f32 v89, v90, v91
	v_add_f32_e32 v164, v92, v164
	v_add_f32_e32 v165, v93, v165
	v_add_f32_e32 v164, v94, v164
	v_add_f32_e32 v165, v95, v165
	v_cvt_pk_bf16_f32 v90, v92, v93
	v_cvt_pk_bf16_f32 v91, v94, v95
	v_cndmask_b32_e64 v88, v88, 0, s[72:73]
	v_cndmask_b32_e64 v89, v89, 0, s[72:73]
	v_cndmask_b32_e64 v90, v90, 0, s[72:73]
	v_cndmask_b32_e64 v91, v91, 0, s[72:73]
	v_exp_f32_e32 v64, v64
	v_exp_f32_e32 v65, v65
	s_waitcnt lgkmcnt(6)
	v_mfma_f32_32x32x16_bf16 v[48:63], v[148:151], v[88:91], v[48:63]
	ds_read_b128 v[148:151], v187 offset:13888
	v_exp_f32_e32 v66, v66
	v_exp_f32_e32 v67, v67
	s_waitcnt lgkmcnt(4)
	v_mfma_f32_32x32x16_bf16 v[32:47], v[124:127], v[88:91], v[32:47]
	ds_read_b128 v[124:127], v187 offset:9312
	v_exp_f32_e32 v68, v68
	v_exp_f32_e32 v69, v69
	v_mfma_f32_32x32x16_bf16 v[238:253], v[108:111], v[136:139], v[238:253]
	v_exp_f32_e32 v70, v70
	v_exp_f32_e32 v71, v71
	v_mfma_f32_32x32x16_bf16 v[222:237], v[112:115], v[136:139], v[222:237]
	v_add_f32_e32 v164, v64, v164
	v_add_f32_e32 v165, v65, v165
	v_add_f32_e32 v164, v66, v164
	v_add_f32_e32 v165, v67, v165
	v_cvt_pk_bf16_f32 v64, v64, v65
	v_cvt_pk_bf16_f32 v65, v66, v67
	v_add_f32_e32 v164, v68, v164
	v_add_f32_e32 v165, v69, v165
	v_add_f32_e32 v164, v70, v164
	v_add_f32_e32 v165, v71, v165
	v_cvt_pk_bf16_f32 v66, v68, v69
	v_cvt_pk_bf16_f32 v67, v70, v71
	v_cndmask_b32_e64 v64, v64, 0, s[72:73]
	v_cndmask_b32_e64 v65, v65, 0, s[72:73]
	v_cndmask_b32_e64 v66, v66, 0, s[72:73]
	v_cndmask_b32_e64 v67, v67, 0, s[72:73]
	v_exp_f32_e32 v72, v72
	v_exp_f32_e32 v73, v73
	s_waitcnt lgkmcnt(4)
	v_mfma_f32_32x32x16_bf16 v[48:63], v[144:147], v[64:67], v[48:63]
	ds_read_b128 v[144:147], v187 offset:13920
	v_exp_f32_e32 v74, v74
	v_exp_f32_e32 v75, v75
	s_waitcnt lgkmcnt(2)
	v_mfma_f32_32x32x16_bf16 v[32:47], v[148:151], v[64:67], v[32:47]
	v_exp_f32_e32 v76, v76
	v_exp_f32_e32 v77, v77
	v_mfma_f32_32x32x16_bf16 v[238:253], v[116:119], v[140:143], v[238:253]
	v_exp_f32_e32 v78, v78
	v_exp_f32_e32 v79, v79
	v_mfma_f32_32x32x16_bf16 v[222:237], v[120:123], v[140:143], v[222:237]
	v_add_f32_e32 v164, v72, v164
	v_add_f32_e32 v165, v73, v165
	v_add_f32_e32 v164, v74, v164
	v_add_f32_e32 v165, v75, v165
	v_cvt_pk_bf16_f32 v72, v72, v73
	v_cvt_pk_bf16_f32 v73, v74, v75
	v_add_f32_e32 v164, v76, v164
	v_add_f32_e32 v165, v77, v165
	v_add_f32_e32 v164, v78, v164
	v_add_f32_e32 v165, v79, v165
	v_cvt_pk_bf16_f32 v74, v76, v77
	v_cvt_pk_bf16_f32 v75, v78, v79
	v_cndmask_b32_e64 v72, v72, 0, s[72:73]
	v_cndmask_b32_e64 v73, v73, 0, s[72:73]
	v_cndmask_b32_e64 v74, v74, 0, s[72:73]
	v_cndmask_b32_e64 v75, v75, 0, s[72:73]
	s_nop 1
	s_waitcnt lgkmcnt(1)
	v_mfma_f32_32x32x16_bf16 v[48:63], v[124:127], v[72:75], v[48:63]
	s_waitcnt lgkmcnt(0)
	v_mfma_f32_32x32x16_bf16 v[32:47], v[144:147], v[72:75], v[32:47]
	v_add_f32_e32 v164, v164, v165
	v_cndmask_b32_e64 v164, v164, 0, s[72:73]
	v_add_f32_e32 v106, v106, v164
	v_cmp_lt_f32_e32 vcc, 0x43800000, v164
	s_cbranch_vccz .Lsel_noresc_0b
	s_nop 15
	s_nop 15
	v_mov_b32_e32 v107, v164
	s_nop 1
	v_permlane32_swap_b32_e32 v164, v107
	v_add_f32_e32 v164, v164, v107
	v_log_f32_e32 v160, v164
	s_nop 0
	v_max_f32_e32 v160, 0, v160
	v_exp_f32_e64 v162, -v160
	v_sub_f32_e32 v2, v2, v160
	v_sub_f32_e32 v3, v3, v160
	v_sub_f32_e32 v4, v4, v160
	v_sub_f32_e32 v5, v5, v160
	v_sub_f32_e32 v6, v6, v160
	v_sub_f32_e32 v7, v7, v160
	v_sub_f32_e32 v8, v8, v160
	v_sub_f32_e32 v9, v9, v160
	v_sub_f32_e32 v10, v10, v160
	v_sub_f32_e32 v11, v11, v160
	v_sub_f32_e32 v12, v12, v160
	v_sub_f32_e32 v13, v13, v160
	v_sub_f32_e32 v14, v14, v160
	v_sub_f32_e32 v15, v15, v160
	v_sub_f32_e32 v16, v16, v160
	v_sub_f32_e32 v17, v17, v160
	v_mul_f32_e32 v106, v106, v162
	v_pk_mul_f32 v[48:49], v[48:49], v[162:163] op_sel_hi:[1,0]
	v_pk_mul_f32 v[32:33], v[32:33], v[162:163] op_sel_hi:[1,0]
	v_pk_mul_f32 v[50:51], v[50:51], v[162:163] op_sel_hi:[1,0]
	v_pk_mul_f32 v[34:35], v[34:35], v[162:163] op_sel_hi:[1,0]
	v_pk_mul_f32 v[52:53], v[52:53], v[162:163] op_sel_hi:[1,0]
	v_pk_mul_f32 v[36:37], v[36:37], v[162:163] op_sel_hi:[1,0]
	v_pk_mul_f32 v[54:55], v[54:55], v[162:163] op_sel_hi:[1,0]
	v_pk_mul_f32 v[38:39], v[38:39], v[162:163] op_sel_hi:[1,0]
	v_pk_mul_f32 v[56:57], v[56:57], v[162:163] op_sel_hi:[1,0]
	v_pk_mul_f32 v[40:41], v[40:41], v[162:163] op_sel_hi:[1,0]
	v_pk_mul_f32 v[58:59], v[58:59], v[162:163] op_sel_hi:[1,0]
	v_pk_mul_f32 v[42:43], v[42:43], v[162:163] op_sel_hi:[1,0]
	v_pk_mul_f32 v[60:61], v[60:61], v[162:163] op_sel_hi:[1,0]
	v_pk_mul_f32 v[44:45], v[44:45], v[162:163] op_sel_hi:[1,0]
	v_pk_mul_f32 v[62:63], v[62:63], v[162:163] op_sel_hi:[1,0]
	v_pk_mul_f32 v[46:47], v[46:47], v[162:163] op_sel_hi:[1,0]
	v_pk_add_f32 v[238:239], v[238:239], v[160:161] op_sel_hi:[1,0] neg_lo:[0,1] neg_hi:[0,1]
	v_pk_add_f32 v[222:223], v[222:223], v[160:161] op_sel_hi:[1,0] neg_lo:[0,1] neg_hi:[0,1]
	v_pk_add_f32 v[240:241], v[240:241], v[160:161] op_sel_hi:[1,0] neg_lo:[0,1] neg_hi:[0,1]
	v_pk_add_f32 v[224:225], v[224:225], v[160:161] op_sel_hi:[1,0] neg_lo:[0,1] neg_hi:[0,1]
	v_pk_add_f32 v[242:243], v[242:243], v[160:161] op_sel_hi:[1,0] neg_lo:[0,1] neg_hi:[0,1]
	v_pk_add_f32 v[226:227], v[226:227], v[160:161] op_sel_hi:[1,0] neg_lo:[0,1] neg_hi:[0,1]
	v_pk_add_f32 v[244:245], v[244:245], v[160:161] op_sel_hi:[1,0] neg_lo:[0,1] neg_hi:[0,1]
	v_pk_add_f32 v[228:229], v[228:229], v[160:161] op_sel_hi:[1,0] neg_lo:[0,1] neg_hi:[0,1]
	v_pk_add_f32 v[246:247], v[246:247], v[160:161] op_sel_hi:[1,0] neg_lo:[0,1] neg_hi:[0,1]
	v_pk_add_f32 v[230:231], v[230:231], v[160:161] op_sel_hi:[1,0] neg_lo:[0,1] neg_hi:[0,1]
	v_pk_add_f32 v[248:249], v[248:249], v[160:161] op_sel_hi:[1,0] neg_lo:[0,1] neg_hi:[0,1]
	v_pk_add_f32 v[232:233], v[232:233], v[160:161] op_sel_hi:[1,0] neg_lo:[0,1] neg_hi:[0,1]
	v_pk_add_f32 v[250:251], v[250:251], v[160:161] op_sel_hi:[1,0] neg_lo:[0,1] neg_hi:[0,1]
	v_pk_add_f32 v[234:235], v[234:235], v[160:161] op_sel_hi:[1,0] neg_lo:[0,1] neg_hi:[0,1]
	v_pk_add_f32 v[252:253], v[252:253], v[160:161] op_sel_hi:[1,0] neg_lo:[0,1] neg_hi:[0,1]
	v_pk_add_f32 v[236:237], v[236:237], v[160:161] op_sel_hi:[1,0] neg_lo:[0,1] neg_hi:[0,1]
	s_nop 1

.Lsel_nodiag_0c:
	v_add_u32_e32 v187, s81, v208
	ds_read_b128 v[124:127], v187 offset:9216
	ds_read_b128 v[144:147], v187 offset:13824
	ds_read_b128 v[148:151], v187 offset:9248
	v_exp_f32_e32 v80, v80
	v_exp_f32_e32 v81, v81
	v_exp_f32_e32 v82, v82
	v_exp_f32_e32 v83, v83
	v_exp_f32_e32 v84, v84
	v_exp_f32_e32 v85, v85
	v_exp_f32_e32 v86, v86
	v_exp_f32_e32 v87, v87
	v_add_f32_e32 v164, 0, v80
	v_add_f32_e32 v165, 0, v81
	v_add_f32_e32 v164, v82, v164
	v_add_f32_e32 v165, v83, v165
	v_cvt_pk_bf16_f32 v80, v80, v81
	v_cvt_pk_bf16_f32 v81, v82, v83
	v_add_f32_e32 v164, v84, v164
	v_add_f32_e32 v165, v85, v165
	v_add_f32_e32 v164, v86, v164
	v_add_f32_e32 v165, v87, v165
	v_cvt_pk_bf16_f32 v82, v84, v85
	v_cvt_pk_bf16_f32 v83, v86, v87
	v_cndmask_b32_e64 v80, v80, 0, s[72:73]
	v_cndmask_b32_e64 v81, v81, 0, s[72:73]
	v_cndmask_b32_e64 v82, v82, 0, s[72:73]
	v_cndmask_b32_e64 v83, v83, 0, s[72:73]
	v_exp_f32_e32 v88, v88
	v_exp_f32_e32 v89, v89
	s_waitcnt lgkmcnt(2)
	v_mfma_f32_32x32x16_bf16 v[48:63], v[124:127], v[80:83], v[48:63]
	ds_read_b128 v[124:127], v187 offset:13856
	v_exp_f32_e32 v90, v90
	v_exp_f32_e32 v91, v91
	s_waitcnt lgkmcnt(2)
	v_mfma_f32_32x32x16_bf16 v[32:47], v[144:147], v[80:83], v[32:47]
	ds_read_b128 v[144:147], v187 offset:9280
	v_exp_f32_e32 v92, v92
	v_exp_f32_e32 v93, v93
	v_exp_f32_e32 v94, v94
	v_exp_f32_e32 v95, v95
	v_add_f32_e32 v164, v88, v164
	v_add_f32_e32 v165, v89, v165
	v_add_f32_e32 v164, v90, v164
	v_add_f32_e32 v165, v91, v165
	v_cvt_pk_bf16_f32 v88, v88, v89
	v_cvt_pk_bf16_f32 v89, v90, v91
	v_add_f32_e32 v164, v92, v164
	v_add_f32_e32 v165, v93, v165
	v_add_f32_e32 v164, v94, v164
	v_add_f32_e32 v165, v95, v165
	v_cvt_pk_bf16_f32 v90, v92, v93
	v_cvt_pk_bf16_f32 v91, v94, v95
	v_cndmask_b32_e64 v88, v88, 0, s[72:73]
	v_cndmask_b32_e64 v89, v89, 0, s[72:73]
	v_cndmask_b32_e64 v90, v90, 0, s[72:73]
	v_cndmask_b32_e64 v91, v91, 0, s[72:73]
	v_exp_f32_e32 v64, v64
	v_exp_f32_e32 v65, v65
	s_waitcnt lgkmcnt(2)
	v_mfma_f32_32x32x16_bf16 v[48:63], v[148:151], v[88:91], v[48:63]
	ds_read_b128 v[148:151], v187 offset:13888
	v_exp_f32_e32 v66, v66
	v_exp_f32_e32 v67, v67
	s_waitcnt lgkmcnt(2)
	v_mfma_f32_32x32x16_bf16 v[32:47], v[124:127], v[88:91], v[32:47]
	ds_read_b128 v[124:127], v187 offset:9312
	v_exp_f32_e32 v68, v68
	v_exp_f32_e32 v69, v69
	v_exp_f32_e32 v70, v70
	v_exp_f32_e32 v71, v71
	v_add_f32_e32 v164, v64, v164
	v_add_f32_e32 v165, v65, v165
	v_add_f32_e32 v164, v66, v164
	v_add_f32_e32 v165, v67, v165
	v_cvt_pk_bf16_f32 v64, v64, v65
	v_cvt_pk_bf16_f32 v65, v66, v67
	v_add_f32_e32 v164, v68, v164
	v_add_f32_e32 v165, v69, v165
	v_add_f32_e32 v164, v70, v164
	v_add_f32_e32 v165, v71, v165
	v_cvt_pk_bf16_f32 v66, v68, v69
	v_cvt_pk_bf16_f32 v67, v70, v71
	v_cndmask_b32_e64 v64, v64, 0, s[72:73]
	v_cndmask_b32_e64 v65, v65, 0, s[72:73]
	v_cndmask_b32_e64 v66, v66, 0, s[72:73]
	v_cndmask_b32_e64 v67, v67, 0, s[72:73]
	v_exp_f32_e32 v72, v72
	v_exp_f32_e32 v73, v73
	s_waitcnt lgkmcnt(2)
	v_mfma_f32_32x32x16_bf16 v[48:63], v[144:147], v[64:67], v[48:63]
	ds_read_b128 v[144:147], v187 offset:13920
	v_exp_f32_e32 v74, v74
	v_exp_f32_e32 v75, v75
	s_waitcnt lgkmcnt(2)
	v_mfma_f32_32x32x16_bf16 v[32:47], v[148:151], v[64:67], v[32:47]
	v_exp_f32_e32 v76, v76
	v_exp_f32_e32 v77, v77
	v_exp_f32_e32 v78, v78
	v_exp_f32_e32 v79, v79
	v_add_f32_e32 v164, v72, v164
	v_add_f32_e32 v165, v73, v165
	v_add_f32_e32 v164, v74, v164
	v_add_f32_e32 v165, v75, v165
	v_cvt_pk_bf16_f32 v72, v72, v73
	v_cvt_pk_bf16_f32 v73, v74, v75
	v_add_f32_e32 v164, v76, v164
	v_add_f32_e32 v165, v77, v165
	v_add_f32_e32 v164, v78, v164
	v_add_f32_e32 v165, v79, v165
	v_cvt_pk_bf16_f32 v74, v76, v77
	v_cvt_pk_bf16_f32 v75, v78, v79
	v_cndmask_b32_e64 v72, v72, 0, s[72:73]
	v_cndmask_b32_e64 v73, v73, 0, s[72:73]
	v_cndmask_b32_e64 v74, v74, 0, s[72:73]
	v_cndmask_b32_e64 v75, v75, 0, s[72:73]
	s_nop 1
	s_waitcnt lgkmcnt(1)
	v_mfma_f32_32x32x16_bf16 v[48:63], v[124:127], v[72:75], v[48:63]
	s_waitcnt lgkmcnt(0)
	v_mfma_f32_32x32x16_bf16 v[32:47], v[144:147], v[72:75], v[32:47]
	v_add_f32_e32 v164, v164, v165
	v_cndmask_b32_e64 v164, v164, 0, s[72:73]
	v_add_f32_e32 v106, v106, v164
	v_cmp_lt_f32_e32 vcc, 0x43800000, v164
	s_cbranch_vccz .Lsel_noresc_0c
	s_nop 15
	s_nop 15
	v_mov_b32_e32 v107, v164
	s_nop 1
	v_permlane32_swap_b32_e32 v164, v107
	v_add_f32_e32 v164, v164, v107
	v_log_f32_e32 v160, v164
	s_nop 0
	v_max_f32_e32 v160, 0, v160
	v_exp_f32_e64 v162, -v160
	v_sub_f32_e32 v2, v2, v160
	v_sub_f32_e32 v3, v3, v160
	v_sub_f32_e32 v4, v4, v160
	v_sub_f32_e32 v5, v5, v160
	v_sub_f32_e32 v6, v6, v160
	v_sub_f32_e32 v7, v7, v160
	v_sub_f32_e32 v8, v8, v160
	v_sub_f32_e32 v9, v9, v160
	v_sub_f32_e32 v10, v10, v160
	v_sub_f32_e32 v11, v11, v160
	v_sub_f32_e32 v12, v12, v160
	v_sub_f32_e32 v13, v13, v160
	v_sub_f32_e32 v14, v14, v160
	v_sub_f32_e32 v15, v15, v160
	v_sub_f32_e32 v16, v16, v160
	v_sub_f32_e32 v17, v17, v160
	v_mul_f32_e32 v106, v106, v162
	v_pk_mul_f32 v[48:49], v[48:49], v[162:163] op_sel_hi:[1,0]
	v_pk_mul_f32 v[32:33], v[32:33], v[162:163] op_sel_hi:[1,0]
	v_pk_mul_f32 v[50:51], v[50:51], v[162:163] op_sel_hi:[1,0]
	v_pk_mul_f32 v[34:35], v[34:35], v[162:163] op_sel_hi:[1,0]
	v_pk_mul_f32 v[52:53], v[52:53], v[162:163] op_sel_hi:[1,0]
	v_pk_mul_f32 v[36:37], v[36:37], v[162:163] op_sel_hi:[1,0]
	v_pk_mul_f32 v[54:55], v[54:55], v[162:163] op_sel_hi:[1,0]
	v_pk_mul_f32 v[38:39], v[38:39], v[162:163] op_sel_hi:[1,0]
	v_pk_mul_f32 v[56:57], v[56:57], v[162:163] op_sel_hi:[1,0]
	v_pk_mul_f32 v[40:41], v[40:41], v[162:163] op_sel_hi:[1,0]
	v_pk_mul_f32 v[58:59], v[58:59], v[162:163] op_sel_hi:[1,0]
	v_pk_mul_f32 v[42:43], v[42:43], v[162:163] op_sel_hi:[1,0]
	v_pk_mul_f32 v[60:61], v[60:61], v[162:163] op_sel_hi:[1,0]
	v_pk_mul_f32 v[44:45], v[44:45], v[162:163] op_sel_hi:[1,0]
	v_pk_mul_f32 v[62:63], v[62:63], v[162:163] op_sel_hi:[1,0]
	v_pk_mul_f32 v[46:47], v[46:47], v[162:163] op_sel_hi:[1,0]
	s_nop 1

.Lsel_nodiag_1b:
	v_add_u32_e32 v187, s81, v208
	ds_read_b128 v[124:127], v187 offset:9216
	ds_read_b128 v[144:147], v187 offset:13824
	ds_read_b128 v[148:151], v187 offset:9248
	v_exp_f32_e32 v238, v238
	v_exp_f32_e32 v239, v239
	v_exp_f32_e32 v240, v240
	v_exp_f32_e32 v241, v241
	s_waitcnt lgkmcnt(6)
	v_mfma_f32_32x32x16_bf16 v[80:95], v[108:111], v[128:131], v[2:17]
	ds_read_b128 v[108:111], v0 offset:64
	v_exp_f32_e32 v242, v242
	v_exp_f32_e32 v243, v243
	v_exp_f32_e32 v244, v244
	v_exp_f32_e32 v245, v245
	s_waitcnt lgkmcnt(6)
	v_mfma_f32_32x32x16_bf16 v[64:79], v[112:115], v[128:131], v[2:17]
	ds_read_b128 v[112:115], v0 offset:4672
	v_add_f32_e32 v164, 0, v238
	v_add_f32_e32 v165, 0, v239
	v_add_f32_e32 v164, v240, v164
	v_add_f32_e32 v165, v241, v165
	v_cvt_pk_bf16_f32 v238, v238, v239
	v_cvt_pk_bf16_f32 v239, v240, v241
	v_add_f32_e32 v164, v242, v164
	v_add_f32_e32 v165, v243, v165
	v_add_f32_e32 v164, v244, v164
	v_add_f32_e32 v165, v245, v165
	v_cvt_pk_bf16_f32 v240, v242, v243
	v_cvt_pk_bf16_f32 v241, v244, v245
	v_cndmask_b32_e64 v238, v238, 0, s[72:73]
	v_cndmask_b32_e64 v239, v239, 0, s[72:73]
	v_cndmask_b32_e64 v240, v240, 0, s[72:73]
	v_cndmask_b32_e64 v241, v241, 0, s[72:73]
	v_exp_f32_e32 v246, v246
	v_exp_f32_e32 v247, v247
	s_waitcnt lgkmcnt(4)
	v_mfma_f32_32x32x16_bf16 v[48:63], v[124:127], v[238:241], v[48:63]
	ds_read_b128 v[124:127], v187 offset:13856
	v_exp_f32_e32 v248, v248
	v_exp_f32_e32 v249, v249
	s_waitcnt lgkmcnt(4)
	v_mfma_f32_32x32x16_bf16 v[32:47], v[144:147], v[238:241], v[32:47]
	ds_read_b128 v[144:147], v187 offset:9280
	v_exp_f32_e32 v250, v250
	v_exp_f32_e32 v251, v251
	v_mfma_f32_32x32x16_bf16 v[80:95], v[116:119], v[132:135], v[80:95]
	ds_read_b128 v[116:119], v0 offset:96
	v_exp_f32_e32 v252, v252
	v_exp_f32_e32 v253, v253
	v_mfma_f32_32x32x16_bf16 v[64:79], v[120:123], v[132:135], v[64:79]
	ds_read_b128 v[120:123], v0 offset:4704
	v_add_f32_e32 v164, v246, v164
	v_add_f32_e32 v165, v247, v165
	v_add_f32_e32 v164, v248, v164
	v_add_f32_e32 v165, v249, v165
	v_cvt_pk_bf16_f32 v246, v246, v247
	v_cvt_pk_bf16_f32 v247, v248, v249
	v_add_f32_e32 v164, v250, v164
	v_add_f32_e32 v165, v251, v165
	v_add_f32_e32 v164, v252, v164
	v_add_f32_e32 v165, v253, v165
	v_cvt_pk_bf16_f32 v248, v250, v251
	v_cvt_pk_bf16_f32 v249, v252, v253
	v_cndmask_b32_e64 v246, v246, 0, s[72:73]
	v_cndmask_b32_e64 v247, v247, 0, s[72:73]
	v_cndmask_b32_e64 v248, v248, 0, s[72:73]
	v_cndmask_b32_e64 v249, v249, 0, s[72:73]
	v_exp_f32_e32 v222, v222
	v_exp_f32_e32 v223, v223
	s_waitcnt lgkmcnt(6)
	v_mfma_f32_32x32x16_bf16 v[48:63], v[148:151], v[246:249], v[48:63]
	ds_read_b128 v[148:151], v187 offset:13888
	v_exp_f32_e32 v224, v224
	v_exp_f32_e32 v225, v225
	s_waitcnt lgkmcnt(4)
	v_mfma_f32_32x32x16_bf16 v[32:47], v[124:127], v[246:249], v[32:47]
	ds_read_b128 v[124:127], v187 offset:9312
	v_exp_f32_e32 v226, v226
	v_exp_f32_e32 v227, v227
	v_mfma_f32_32x32x16_bf16 v[80:95], v[108:111], v[136:139], v[80:95]
	v_exp_f32_e32 v228, v228
	v_exp_f32_e32 v229, v229
	v_mfma_f32_32x32x16_bf16 v[64:79], v[112:115], v[136:139], v[64:79]
	v_add_f32_e32 v164, v222, v164
	v_add_f32_e32 v165, v223, v165
	v_add_f32_e32 v164, v224, v164
	v_add_f32_e32 v165, v225, v165
	v_cvt_pk_bf16_f32 v222, v222, v223
	v_cvt_pk_bf16_f32 v223, v224, v225
	v_add_f32_e32 v164, v226, v164
	v_add_f32_e32 v165, v227, v165
	v_add_f32_e32 v164, v228, v164
	v_add_f32_e32 v165, v229, v165
	v_cvt_pk_bf16_f32 v224, v226, v227
	v_cvt_pk_bf16_f32 v225, v228, v229
	v_cndmask_b32_e64 v222, v222, 0, s[72:73]
	v_cndmask_b32_e64 v223, v223, 0, s[72:73]
	v_cndmask_b32_e64 v224, v224, 0, s[72:73]
	v_cndmask_b32_e64 v225, v225, 0, s[72:73]
	v_exp_f32_e32 v230, v230
	v_exp_f32_e32 v231, v231
	s_waitcnt lgkmcnt(4)
	v_mfma_f32_32x32x16_bf16 v[48:63], v[144:147], v[222:225], v[48:63]
	ds_read_b128 v[144:147], v187 offset:13920
	v_exp_f32_e32 v232, v232
	v_exp_f32_e32 v233, v233
	s_waitcnt lgkmcnt(2)
	v_mfma_f32_32x32x16_bf16 v[32:47], v[148:151], v[222:225], v[32:47]
	v_exp_f32_e32 v234, v234
	v_exp_f32_e32 v235, v235
	v_mfma_f32_32x32x16_bf16 v[80:95], v[116:119], v[140:143], v[80:95]
	v_exp_f32_e32 v236, v236
	v_exp_f32_e32 v237, v237
	v_mfma_f32_32x32x16_bf16 v[64:79], v[120:123], v[140:143], v[64:79]
	v_add_f32_e32 v164, v230, v164
	v_add_f32_e32 v165, v231, v165
	v_add_f32_e32 v164, v232, v164
	v_add_f32_e32 v165, v233, v165
	v_cvt_pk_bf16_f32 v230, v230, v231
	v_cvt_pk_bf16_f32 v231, v232, v233
	v_add_f32_e32 v164, v234, v164
	v_add_f32_e32 v165, v235, v165
	v_add_f32_e32 v164, v236, v164
	v_add_f32_e32 v165, v237, v165
	v_cvt_pk_bf16_f32 v232, v234, v235
	v_cvt_pk_bf16_f32 v233, v236, v237
	v_cndmask_b32_e64 v230, v230, 0, s[72:73]
	v_cndmask_b32_e64 v231, v231, 0, s[72:73]
	v_cndmask_b32_e64 v232, v232, 0, s[72:73]
	v_cndmask_b32_e64 v233, v233, 0, s[72:73]
	s_nop 1
	s_waitcnt lgkmcnt(1)
	v_mfma_f32_32x32x16_bf16 v[48:63], v[124:127], v[230:233], v[48:63]
	s_waitcnt lgkmcnt(0)
	v_mfma_f32_32x32x16_bf16 v[32:47], v[144:147], v[230:233], v[32:47]
	v_add_f32_e32 v164, v164, v165
	v_cndmask_b32_e64 v164, v164, 0, s[72:73]
	v_add_f32_e32 v106, v106, v164
	v_cmp_lt_f32_e32 vcc, 0x43800000, v164
	s_cbranch_vccz .Lsel_noresc_1b
	s_nop 15
	s_nop 15
	v_mov_b32_e32 v107, v164
	s_nop 1
	v_permlane32_swap_b32_e32 v164, v107
	v_add_f32_e32 v164, v164, v107
	v_log_f32_e32 v160, v164
	s_nop 0
	v_max_f32_e32 v160, 0, v160
	v_exp_f32_e64 v162, -v160
	v_sub_f32_e32 v2, v2, v160
	v_sub_f32_e32 v3, v3, v160
	v_sub_f32_e32 v4, v4, v160
	v_sub_f32_e32 v5, v5, v160
	v_sub_f32_e32 v6, v6, v160
	v_sub_f32_e32 v7, v7, v160
	v_sub_f32_e32 v8, v8, v160
	v_sub_f32_e32 v9, v9, v160
	v_sub_f32_e32 v10, v10, v160
	v_sub_f32_e32 v11, v11, v160
	v_sub_f32_e32 v12, v12, v160
	v_sub_f32_e32 v13, v13, v160
	v_sub_f32_e32 v14, v14, v160
	v_sub_f32_e32 v15, v15, v160
	v_sub_f32_e32 v16, v16, v160
	v_sub_f32_e32 v17, v17, v160
	v_mul_f32_e32 v106, v106, v162
	v_pk_mul_f32 v[48:49], v[48:49], v[162:163] op_sel_hi:[1,0]
	v_pk_mul_f32 v[32:33], v[32:33], v[162:163] op_sel_hi:[1,0]
	v_pk_mul_f32 v[50:51], v[50:51], v[162:163] op_sel_hi:[1,0]
	v_pk_mul_f32 v[34:35], v[34:35], v[162:163] op_sel_hi:[1,0]
	v_pk_mul_f32 v[52:53], v[52:53], v[162:163] op_sel_hi:[1,0]
	v_pk_mul_f32 v[36:37], v[36:37], v[162:163] op_sel_hi:[1,0]
	v_pk_mul_f32 v[54:55], v[54:55], v[162:163] op_sel_hi:[1,0]
	v_pk_mul_f32 v[38:39], v[38:39], v[162:163] op_sel_hi:[1,0]
	v_pk_mul_f32 v[56:57], v[56:57], v[162:163] op_sel_hi:[1,0]
	v_pk_mul_f32 v[40:41], v[40:41], v[162:163] op_sel_hi:[1,0]
	v_pk_mul_f32 v[58:59], v[58:59], v[162:163] op_sel_hi:[1,0]
	v_pk_mul_f32 v[42:43], v[42:43], v[162:163] op_sel_hi:[1,0]
	v_pk_mul_f32 v[60:61], v[60:61], v[162:163] op_sel_hi:[1,0]
	v_pk_mul_f32 v[44:45], v[44:45], v[162:163] op_sel_hi:[1,0]
	v_pk_mul_f32 v[62:63], v[62:63], v[162:163] op_sel_hi:[1,0]
	v_pk_mul_f32 v[46:47], v[46:47], v[162:163] op_sel_hi:[1,0]
	v_pk_add_f32 v[80:81], v[80:81], v[160:161] op_sel_hi:[1,0] neg_lo:[0,1] neg_hi:[0,1]
	v_pk_add_f32 v[64:65], v[64:65], v[160:161] op_sel_hi:[1,0] neg_lo:[0,1] neg_hi:[0,1]
	v_pk_add_f32 v[82:83], v[82:83], v[160:161] op_sel_hi:[1,0] neg_lo:[0,1] neg_hi:[0,1]
	v_pk_add_f32 v[66:67], v[66:67], v[160:161] op_sel_hi:[1,0] neg_lo:[0,1] neg_hi:[0,1]
	v_pk_add_f32 v[84:85], v[84:85], v[160:161] op_sel_hi:[1,0] neg_lo:[0,1] neg_hi:[0,1]
	v_pk_add_f32 v[68:69], v[68:69], v[160:161] op_sel_hi:[1,0] neg_lo:[0,1] neg_hi:[0,1]
	v_pk_add_f32 v[86:87], v[86:87], v[160:161] op_sel_hi:[1,0] neg_lo:[0,1] neg_hi:[0,1]
	v_pk_add_f32 v[70:71], v[70:71], v[160:161] op_sel_hi:[1,0] neg_lo:[0,1] neg_hi:[0,1]
	v_pk_add_f32 v[88:89], v[88:89], v[160:161] op_sel_hi:[1,0] neg_lo:[0,1] neg_hi:[0,1]
	v_pk_add_f32 v[72:73], v[72:73], v[160:161] op_sel_hi:[1,0] neg_lo:[0,1] neg_hi:[0,1]
	v_pk_add_f32 v[90:91], v[90:91], v[160:161] op_sel_hi:[1,0] neg_lo:[0,1] neg_hi:[0,1]
	v_pk_add_f32 v[74:75], v[74:75], v[160:161] op_sel_hi:[1,0] neg_lo:[0,1] neg_hi:[0,1]
	v_pk_add_f32 v[92:93], v[92:93], v[160:161] op_sel_hi:[1,0] neg_lo:[0,1] neg_hi:[0,1]
	v_pk_add_f32 v[76:77], v[76:77], v[160:161] op_sel_hi:[1,0] neg_lo:[0,1] neg_hi:[0,1]
	v_pk_add_f32 v[94:95], v[94:95], v[160:161] op_sel_hi:[1,0] neg_lo:[0,1] neg_hi:[0,1]
	v_pk_add_f32 v[78:79], v[78:79], v[160:161] op_sel_hi:[1,0] neg_lo:[0,1] neg_hi:[0,1]
	s_nop 1

.Lsel_nodiag_1c:
	v_add_u32_e32 v187, s81, v208
	ds_read_b128 v[124:127], v187 offset:9216
	ds_read_b128 v[144:147], v187 offset:13824
	ds_read_b128 v[148:151], v187 offset:9248
	v_exp_f32_e32 v238, v238
	v_exp_f32_e32 v239, v239
	v_exp_f32_e32 v240, v240
	v_exp_f32_e32 v241, v241
	v_exp_f32_e32 v242, v242
	v_exp_f32_e32 v243, v243
	v_exp_f32_e32 v244, v244
	v_exp_f32_e32 v245, v245
	v_add_f32_e32 v164, 0, v238
	v_add_f32_e32 v165, 0, v239
	v_add_f32_e32 v164, v240, v164
	v_add_f32_e32 v165, v241, v165
	v_cvt_pk_bf16_f32 v238, v238, v239
	v_cvt_pk_bf16_f32 v239, v240, v241
	v_add_f32_e32 v164, v242, v164
	v_add_f32_e32 v165, v243, v165
	v_add_f32_e32 v164, v244, v164
	v_add_f32_e32 v165, v245, v165
	v_cvt_pk_bf16_f32 v240, v242, v243
	v_cvt_pk_bf16_f32 v241, v244, v245
	v_cndmask_b32_e64 v238, v238, 0, s[72:73]
	v_cndmask_b32_e64 v239, v239, 0, s[72:73]
	v_cndmask_b32_e64 v240, v240, 0, s[72:73]
	v_cndmask_b32_e64 v241, v241, 0, s[72:73]
	v_exp_f32_e32 v246, v246
	v_exp_f32_e32 v247, v247
	s_waitcnt lgkmcnt(2)
	v_mfma_f32_32x32x16_bf16 v[48:63], v[124:127], v[238:241], v[48:63]
	ds_read_b128 v[124:127], v187 offset:13856
	v_exp_f32_e32 v248, v248
	v_exp_f32_e32 v249, v249
	s_waitcnt lgkmcnt(2)
	v_mfma_f32_32x32x16_bf16 v[32:47], v[144:147], v[238:241], v[32:47]
	ds_read_b128 v[144:147], v187 offset:9280
	v_exp_f32_e32 v250, v250
	v_exp_f32_e32 v251, v251
	v_exp_f32_e32 v252, v252
	v_exp_f32_e32 v253, v253
	v_add_f32_e32 v164, v246, v164
	v_add_f32_e32 v165, v247, v165
	v_add_f32_e32 v164, v248, v164
	v_add_f32_e32 v165, v249, v165
	v_cvt_pk_bf16_f32 v246, v246, v247
	v_cvt_pk_bf16_f32 v247, v248, v249
	v_add_f32_e32 v164, v250, v164
	v_add_f32_e32 v165, v251, v165
	v_add_f32_e32 v164, v252, v164
	v_add_f32_e32 v165, v253, v165
	v_cvt_pk_bf16_f32 v248, v250, v251
	v_cvt_pk_bf16_f32 v249, v252, v253
	v_cndmask_b32_e64 v246, v246, 0, s[72:73]
	v_cndmask_b32_e64 v247, v247, 0, s[72:73]
	v_cndmask_b32_e64 v248, v248, 0, s[72:73]
	v_cndmask_b32_e64 v249, v249, 0, s[72:73]
	v_exp_f32_e32 v222, v222
	v_exp_f32_e32 v223, v223
	s_waitcnt lgkmcnt(2)
	v_mfma_f32_32x32x16_bf16 v[48:63], v[148:151], v[246:249], v[48:63]
	ds_read_b128 v[148:151], v187 offset:13888
	v_exp_f32_e32 v224, v224
	v_exp_f32_e32 v225, v225
	s_waitcnt lgkmcnt(2)
	v_mfma_f32_32x32x16_bf16 v[32:47], v[124:127], v[246:249], v[32:47]
	ds_read_b128 v[124:127], v187 offset:9312
	v_exp_f32_e32 v226, v226
	v_exp_f32_e32 v227, v227
	v_exp_f32_e32 v228, v228
	v_exp_f32_e32 v229, v229
	v_add_f32_e32 v164, v222, v164
	v_add_f32_e32 v165, v223, v165
	v_add_f32_e32 v164, v224, v164
	v_add_f32_e32 v165, v225, v165
	v_cvt_pk_bf16_f32 v222, v222, v223
	v_cvt_pk_bf16_f32 v223, v224, v225
	v_add_f32_e32 v164, v226, v164
	v_add_f32_e32 v165, v227, v165
	v_add_f32_e32 v164, v228, v164
	v_add_f32_e32 v165, v229, v165
	v_cvt_pk_bf16_f32 v224, v226, v227
	v_cvt_pk_bf16_f32 v225, v228, v229
	v_cndmask_b32_e64 v222, v222, 0, s[72:73]
	v_cndmask_b32_e64 v223, v223, 0, s[72:73]
	v_cndmask_b32_e64 v224, v224, 0, s[72:73]
	v_cndmask_b32_e64 v225, v225, 0, s[72:73]
	v_exp_f32_e32 v230, v230
	v_exp_f32_e32 v231, v231
	s_waitcnt lgkmcnt(2)
	v_mfma_f32_32x32x16_bf16 v[48:63], v[144:147], v[222:225], v[48:63]
	ds_read_b128 v[144:147], v187 offset:13920
	v_exp_f32_e32 v232, v232
	v_exp_f32_e32 v233, v233
	s_waitcnt lgkmcnt(2)
	v_mfma_f32_32x32x16_bf16 v[32:47], v[148:151], v[222:225], v[32:47]
	v_exp_f32_e32 v234, v234
	v_exp_f32_e32 v235, v235
	v_exp_f32_e32 v236, v236
	v_exp_f32_e32 v237, v237
	v_add_f32_e32 v164, v230, v164
	v_add_f32_e32 v165, v231, v165
	v_add_f32_e32 v164, v232, v164
	v_add_f32_e32 v165, v233, v165
	v_cvt_pk_bf16_f32 v230, v230, v231
	v_cvt_pk_bf16_f32 v231, v232, v233
	v_add_f32_e32 v164, v234, v164
	v_add_f32_e32 v165, v235, v165
	v_add_f32_e32 v164, v236, v164
	v_add_f32_e32 v165, v237, v165
	v_cvt_pk_bf16_f32 v232, v234, v235
	v_cvt_pk_bf16_f32 v233, v236, v237
	v_cndmask_b32_e64 v230, v230, 0, s[72:73]
	v_cndmask_b32_e64 v231, v231, 0, s[72:73]
	v_cndmask_b32_e64 v232, v232, 0, s[72:73]
	v_cndmask_b32_e64 v233, v233, 0, s[72:73]
	s_nop 1
	s_waitcnt lgkmcnt(1)
	v_mfma_f32_32x32x16_bf16 v[48:63], v[124:127], v[230:233], v[48:63]
	s_waitcnt lgkmcnt(0)
	v_mfma_f32_32x32x16_bf16 v[32:47], v[144:147], v[230:233], v[32:47]
	v_add_f32_e32 v164, v164, v165
	v_cndmask_b32_e64 v164, v164, 0, s[72:73]
	v_add_f32_e32 v106, v106, v164
	v_cmp_lt_f32_e32 vcc, 0x43800000, v164
	s_cbranch_vccz .Lsel_noresc_1c
	s_nop 15
	s_nop 15
	v_mov_b32_e32 v107, v164
	s_nop 1
	v_permlane32_swap_b32_e32 v164, v107
	v_add_f32_e32 v164, v164, v107
	v_log_f32_e32 v160, v164
	s_nop 0
	v_max_f32_e32 v160, 0, v160
	v_exp_f32_e64 v162, -v160
	v_sub_f32_e32 v2, v2, v160
	v_sub_f32_e32 v3, v3, v160
	v_sub_f32_e32 v4, v4, v160
	v_sub_f32_e32 v5, v5, v160
	v_sub_f32_e32 v6, v6, v160
	v_sub_f32_e32 v7, v7, v160
	v_sub_f32_e32 v8, v8, v160
	v_sub_f32_e32 v9, v9, v160
	v_sub_f32_e32 v10, v10, v160
	v_sub_f32_e32 v11, v11, v160
	v_sub_f32_e32 v12, v12, v160
	v_sub_f32_e32 v13, v13, v160
	v_sub_f32_e32 v14, v14, v160
	v_sub_f32_e32 v15, v15, v160
	v_sub_f32_e32 v16, v16, v160
	v_sub_f32_e32 v17, v17, v160
	v_mul_f32_e32 v106, v106, v162
	v_pk_mul_f32 v[48:49], v[48:49], v[162:163] op_sel_hi:[1,0]
	v_pk_mul_f32 v[32:33], v[32:33], v[162:163] op_sel_hi:[1,0]
	v_pk_mul_f32 v[50:51], v[50:51], v[162:163] op_sel_hi:[1,0]
	v_pk_mul_f32 v[34:35], v[34:35], v[162:163] op_sel_hi:[1,0]
	v_pk_mul_f32 v[52:53], v[52:53], v[162:163] op_sel_hi:[1,0]
	v_pk_mul_f32 v[36:37], v[36:37], v[162:163] op_sel_hi:[1,0]
	v_pk_mul_f32 v[54:55], v[54:55], v[162:163] op_sel_hi:[1,0]
	v_pk_mul_f32 v[38:39], v[38:39], v[162:163] op_sel_hi:[1,0]
	v_pk_mul_f32 v[56:57], v[56:57], v[162:163] op_sel_hi:[1,0]
	v_pk_mul_f32 v[40:41], v[40:41], v[162:163] op_sel_hi:[1,0]
	v_pk_mul_f32 v[58:59], v[58:59], v[162:163] op_sel_hi:[1,0]
	v_pk_mul_f32 v[42:43], v[42:43], v[162:163] op_sel_hi:[1,0]
	v_pk_mul_f32 v[60:61], v[60:61], v[162:163] op_sel_hi:[1,0]
	v_pk_mul_f32 v[44:45], v[44:45], v[162:163] op_sel_hi:[1,0]
	v_pk_mul_f32 v[62:63], v[62:63], v[162:163] op_sel_hi:[1,0]
	v_pk_mul_f32 v[46:47], v[46:47], v[162:163] op_sel_hi:[1,0]
	s_nop 1
